# attention softmax: the 16 packed v_pk_fma_f32 between P.V MFMAs split into 32 single v_fma_f32 (bit-identical)
# speedup vs baseline: 1.0027x; 1.0027x over previous
.Lat_nme:
	v_add_u32_e32 v184, 0xffffffc0, v184
	v_max_f32_e32 v200, v65, v65
	s_waitcnt lgkmcnt(6)
	v_mfma_f32_32x32x16_bf16 v[32:47], v[204:207], v[220:223], v[32:47]
	ds_read_b64_tr_b16 v[220:221], v165 offset:512
	ds_read_b64_tr_b16 v[222:223], v165 offset:2560
	v_max_f32_e32 v201, v64, v64
	v_max_f32_e32 v200, v201, v200
	v_max3_f32 v200, v200, v66, v67
	v_max3_f32 v200, v200, v68, v69
	v_max3_f32 v200, v200, v70, v71
	s_waitcnt lgkmcnt(6)
	v_mfma_f32_32x32x16_bf16 v[32:47], v[208:211], v[224:227], v[32:47]
	ds_read_b64_tr_b16 v[224:225], v165 offset:4608
	ds_read_b64_tr_b16 v[226:227], v165 offset:6656
	v_max3_f32 v200, v200, v72, v73
	v_max3_f32 v200, v200, v74, v75
	v_max3_f32 v200, v200, v76, v77
	v_max3_f32 v200, v200, v78, v79
	v_max3_f32 v200, v200, v80, v81
	s_waitcnt lgkmcnt(6)
	v_mfma_f32_32x32x16_bf16 v[32:47], v[212:215], v[228:231], v[32:47]
	ds_read_b64_tr_b16 v[228:229], v165 offset:8704
	ds_read_b64_tr_b16 v[230:231], v165 offset:10752
	v_max3_f32 v200, v200, v82, v83
	v_max3_f32 v200, v200, v84, v85
	v_max3_f32 v200, v200, v86, v87
	v_max3_f32 v200, v200, v88, v89
	s_waitcnt lgkmcnt(6)
	v_mfma_f32_32x32x16_bf16 v[32:47], v[216:219], v[232:235], v[32:47]
	ds_read_b64_tr_b16 v[232:233], v165 offset:12800
	ds_read_b64_tr_b16 v[234:235], v165 offset:14848
	v_max3_f32 v200, v200, v90, v91
	v_max3_f32 v200, v200, v92, v93
	v_max3_f32 v200, v200, v94, v95
	v_mov_b32_e32 v201, v200
	s_nop 1
	s_waitcnt lgkmcnt(6)
	v_mfma_f32_32x32x16_bf16 v[48:63], v[204:207], v[220:223], v[48:63]
	ds_read_b64_tr_b16 v[220:221], v165 offset:1024
	ds_read_b64_tr_b16 v[222:223], v165 offset:3072
	v_permlane32_swap_b32_e32 v200, v201
	v_max_f32_e32 v201, v201, v201
	v_max_f32_e32 v200, v200, v200
	v_max_f32_e32 v200, v200, v201
	v_sub_f32_e32 v201, v200, v203
	s_waitcnt lgkmcnt(6)
	v_mfma_f32_32x32x16_bf16 v[48:63], v[208:211], v[224:227], v[48:63]
	ds_read_b64_tr_b16 v[224:225], v165 offset:5120
	ds_read_b64_tr_b16 v[226:227], v165 offset:7168
	v_mul_f32_e32 v201, 0x3db504f3, v201
	v_cmp_ge_f32_e32 vcc, 0x41000000, v201
	v_max_f32_e32 v201, v203, v203
	v_max_f32_e32 v200, v201, v200
	s_waitcnt lgkmcnt(6)
	v_mfma_f32_32x32x16_bf16 v[48:63], v[212:215], v[228:231], v[48:63]
	ds_read_b64_tr_b16 v[228:229], v165 offset:9216
	ds_read_b64_tr_b16 v[230:231], v165 offset:11264
	v_sub_f32_e32 v201, v203, v200
	v_mul_f32_e32 v201, 0x3e0293ee, v201
	v_exp_f32_e32 v201, v201
	s_cmp_eq_u64 vcc, exec
	s_cselect_b64 s[44:45], -1, 0
	s_waitcnt lgkmcnt(6)
	v_mfma_f32_32x32x16_bf16 v[48:63], v[216:219], v[232:235], v[48:63]
	ds_read_b64_tr_b16 v[232:233], v165 offset:13312
	ds_read_b64_tr_b16 v[234:235], v165 offset:15360
	v_cndmask_b32_e64 v202, v201, 1.0, s[44:45]
	v_cndmask_b32_e64 v203, v200, v203, s[44:45]
	v_mul_f32_e32 v248, 0xbe0293ee, v203
	v_fma_f32 v64, v64, s10, v248
	v_fma_f32 v65, v65, s10, v248
	v_fma_f32 v66, v66, s10, v248
	v_fma_f32 v67, v67, s10, v248
	s_waitcnt lgkmcnt(6)
	v_mfma_f32_32x32x16_bf16 v[16:31], v[204:207], v[220:223], v[16:31]
	ds_read_b64_tr_b16 v[220:221], v165 offset:1536
	ds_read_b64_tr_b16 v[222:223], v165 offset:3584
	v_fma_f32 v68, v68, s10, v248
	v_fma_f32 v69, v69, s10, v248
	v_fma_f32 v70, v70, s10, v248
	v_fma_f32 v71, v71, s10, v248
	v_fma_f32 v72, v72, s10, v248
	v_fma_f32 v73, v73, s10, v248
	v_fma_f32 v74, v74, s10, v248
	v_fma_f32 v75, v75, s10, v248
	s_waitcnt lgkmcnt(6)
	v_mfma_f32_32x32x16_bf16 v[16:31], v[208:211], v[224:227], v[16:31]
	ds_read_b64_tr_b16 v[224:225], v165 offset:5632
	ds_read_b64_tr_b16 v[226:227], v165 offset:7680
	v_fma_f32 v76, v76, s10, v248
	v_fma_f32 v77, v77, s10, v248
	v_fma_f32 v78, v78, s10, v248
	v_fma_f32 v79, v79, s10, v248
	v_fma_f32 v80, v80, s10, v248
	v_fma_f32 v81, v81, s10, v248
	v_fma_f32 v82, v82, s10, v248
	v_fma_f32 v83, v83, s10, v248
	v_fma_f32 v84, v84, s10, v248
	v_fma_f32 v85, v85, s10, v248
	s_waitcnt lgkmcnt(6)
	v_mfma_f32_32x32x16_bf16 v[16:31], v[212:215], v[228:231], v[16:31]
	ds_read_b64_tr_b16 v[228:229], v165 offset:9728
	ds_read_b64_tr_b16 v[230:231], v165 offset:11776
	v_fma_f32 v86, v86, s10, v248
	v_fma_f32 v87, v87, s10, v248
	v_fma_f32 v88, v88, s10, v248
	v_fma_f32 v89, v89, s10, v248
	v_fma_f32 v90, v90, s10, v248
	v_fma_f32 v91, v91, s10, v248
	v_fma_f32 v92, v92, s10, v248
	v_fma_f32 v93, v93, s10, v248
	v_fma_f32 v94, v94, s10, v248
	v_fma_f32 v95, v95, s10, v248
	s_waitcnt lgkmcnt(6)
	v_mfma_f32_32x32x16_bf16 v[16:31], v[216:219], v[232:235], v[16:31]
	ds_read_b64_tr_b16 v[232:233], v165 offset:13824
	ds_read_b64_tr_b16 v[234:235], v165 offset:15872
	v_exp_f32_e32 v64, v64
	v_exp_f32_e32 v65, v65
	v_exp_f32_e32 v66, v66
	v_exp_f32_e32 v67, v67
	s_waitcnt lgkmcnt(6)
	v_mfma_f32_32x32x16_bf16 v[0:15], v[204:207], v[220:223], v[0:15]
	v_exp_f32_e32 v68, v68
	v_exp_f32_e32 v69, v69
	v_pk_add_f32 v[170:171], v[64:65], v[66:67]
	v_exp_f32_e32 v70, v70
	v_exp_f32_e32 v71, v71
	s_waitcnt lgkmcnt(4)
	v_mfma_f32_32x32x16_bf16 v[0:15], v[208:211], v[224:227], v[0:15]
	v_pk_add_f32 v[170:171], v[170:171], v[68:69]
	v_exp_f32_e32 v72, v72
	v_exp_f32_e32 v73, v73
	v_pk_add_f32 v[170:171], v[170:171], v[70:71]
	v_exp_f32_e32 v74, v74
	s_waitcnt lgkmcnt(2)
	v_mfma_f32_32x32x16_bf16 v[0:15], v[212:215], v[228:231], v[0:15]
	v_exp_f32_e32 v75, v75
	v_pk_add_f32 v[170:171], v[170:171], v[72:73]
	v_exp_f32_e32 v76, v76
	v_exp_f32_e32 v77, v77
	s_waitcnt lgkmcnt(0)
	v_mfma_f32_32x32x16_bf16 v[0:15], v[216:219], v[232:235], v[0:15]
	v_pk_add_f32 v[170:171], v[170:171], v[74:75]
	v_exp_f32_e32 v78, v78
	v_exp_f32_e32 v79, v79
	v_pk_add_f32 v[170:171], v[170:171], v[76:77]
	v_cmp_gt_f32_e32 vcc, 1.0, v202
	s_cbranch_vccz .Lat_nre
	s_nop 7
	s_nop 7
	s_and_saveexec_b64 s[4:5], s[0:1]
	ds_write_b32 v183, v202
	s_or_b64 exec, exec, s[4:5]
	s_waitcnt lgkmcnt(0)
	ds_read_b128 v[244:247], v177 offset:0
	s_waitcnt lgkmcnt(0)
	v_pk_mul_f32 v[32:33], v[32:33], v[244:245]
	v_pk_mul_f32 v[34:35], v[34:35], v[246:247]
	v_pk_mul_f32 v[48:49], v[48:49], v[244:245]
	v_pk_mul_f32 v[50:51], v[50:51], v[246:247]
	v_pk_mul_f32 v[16:17], v[16:17], v[244:245]
	v_pk_mul_f32 v[18:19], v[18:19], v[246:247]
	v_pk_mul_f32 v[0:1], v[0:1], v[244:245]
	v_pk_mul_f32 v[2:3], v[2:3], v[246:247]
	ds_read_b128 v[244:247], v177 offset:32
	s_waitcnt lgkmcnt(0)
	v_pk_mul_f32 v[36:37], v[36:37], v[244:245]
	v_pk_mul_f32 v[38:39], v[38:39], v[246:247]
	v_pk_mul_f32 v[52:53], v[52:53], v[244:245]
	v_pk_mul_f32 v[54:55], v[54:55], v[246:247]
	v_pk_mul_f32 v[20:21], v[20:21], v[244:245]
	v_pk_mul_f32 v[22:23], v[22:23], v[246:247]
	v_pk_mul_f32 v[4:5], v[4:5], v[244:245]
	v_pk_mul_f32 v[6:7], v[6:7], v[246:247]
	ds_read_b128 v[244:247], v177 offset:64
	s_waitcnt lgkmcnt(0)
	v_pk_mul_f32 v[40:41], v[40:41], v[244:245]
	v_pk_mul_f32 v[42:43], v[42:43], v[246:247]
	v_pk_mul_f32 v[56:57], v[56:57], v[244:245]
	v_pk_mul_f32 v[58:59], v[58:59], v[246:247]
	v_pk_mul_f32 v[24:25], v[24:25], v[244:245]
	v_pk_mul_f32 v[26:27], v[26:27], v[246:247]
	v_pk_mul_f32 v[8:9], v[8:9], v[244:245]
	v_pk_mul_f32 v[10:11], v[10:11], v[246:247]
	ds_read_b128 v[244:247], v177 offset:96
	s_waitcnt lgkmcnt(0)
	v_pk_mul_f32 v[44:45], v[44:45], v[244:245]
	v_pk_mul_f32 v[46:47], v[46:47], v[246:247]
	v_pk_mul_f32 v[60:61], v[60:61], v[244:245]
	v_pk_mul_f32 v[62:63], v[62:63], v[246:247]
	v_pk_mul_f32 v[28:29], v[28:29], v[244:245]
	v_pk_mul_f32 v[30:31], v[30:31], v[246:247]
	v_pk_mul_f32 v[12:13], v[12:13], v[244:245]
	v_pk_mul_f32 v[14:15], v[14:15], v[246:247]

.Lat_nmo:
	v_add_u32_e32 v184, 0xffffffc0, v184
	v_max_f32_e32 v200, v205, v205
	s_waitcnt lgkmcnt(6)
	v_mfma_f32_32x32x16_bf16 v[32:47], v[64:67], v[80:83], v[32:47]
	ds_read_b64_tr_b16 v[80:81], v165 offset:512
	ds_read_b64_tr_b16 v[82:83], v165 offset:2560
	v_max_f32_e32 v201, v204, v204
	v_max_f32_e32 v200, v201, v200
	v_max3_f32 v200, v200, v206, v207
	v_max3_f32 v200, v200, v208, v209
	v_max3_f32 v200, v200, v210, v211
	s_waitcnt lgkmcnt(6)
	v_mfma_f32_32x32x16_bf16 v[32:47], v[68:71], v[84:87], v[32:47]
	ds_read_b64_tr_b16 v[84:85], v165 offset:4608
	ds_read_b64_tr_b16 v[86:87], v165 offset:6656
	v_max3_f32 v200, v200, v212, v213
	v_max3_f32 v200, v200, v214, v215
	v_max3_f32 v200, v200, v216, v217
	v_max3_f32 v200, v200, v218, v219
	v_max3_f32 v200, v200, v220, v221
	s_waitcnt lgkmcnt(6)
	v_mfma_f32_32x32x16_bf16 v[32:47], v[72:75], v[88:91], v[32:47]
	ds_read_b64_tr_b16 v[88:89], v165 offset:8704
	ds_read_b64_tr_b16 v[90:91], v165 offset:10752
	v_max3_f32 v200, v200, v222, v223
	v_max3_f32 v200, v200, v224, v225
	v_max3_f32 v200, v200, v226, v227
	v_max3_f32 v200, v200, v228, v229
	s_waitcnt lgkmcnt(6)
	v_mfma_f32_32x32x16_bf16 v[32:47], v[76:79], v[92:95], v[32:47]
	ds_read_b64_tr_b16 v[92:93], v165 offset:12800
	ds_read_b64_tr_b16 v[94:95], v165 offset:14848
	v_max3_f32 v200, v200, v230, v231
	v_max3_f32 v200, v200, v232, v233
	v_max3_f32 v200, v200, v234, v235
	v_mov_b32_e32 v201, v200
	s_nop 1
	s_waitcnt lgkmcnt(6)
	v_mfma_f32_32x32x16_bf16 v[48:63], v[64:67], v[80:83], v[48:63]
	ds_read_b64_tr_b16 v[80:81], v165 offset:1024
	ds_read_b64_tr_b16 v[82:83], v165 offset:3072
	v_permlane32_swap_b32_e32 v200, v201
	v_max_f32_e32 v201, v201, v201
	v_max_f32_e32 v200, v200, v200
	v_max_f32_e32 v200, v200, v201
	v_sub_f32_e32 v201, v200, v203
	s_waitcnt lgkmcnt(6)
	v_mfma_f32_32x32x16_bf16 v[48:63], v[68:71], v[84:87], v[48:63]
	ds_read_b64_tr_b16 v[84:85], v165 offset:5120
	ds_read_b64_tr_b16 v[86:87], v165 offset:7168
	v_mul_f32_e32 v201, 0x3db504f3, v201
	v_cmp_ge_f32_e32 vcc, 0x41000000, v201
	v_max_f32_e32 v201, v203, v203
	v_max_f32_e32 v200, v201, v200
	s_waitcnt lgkmcnt(6)
	v_mfma_f32_32x32x16_bf16 v[48:63], v[72:75], v[88:91], v[48:63]
	ds_read_b64_tr_b16 v[88:89], v165 offset:9216
	ds_read_b64_tr_b16 v[90:91], v165 offset:11264
	v_sub_f32_e32 v201, v203, v200
	v_mul_f32_e32 v201, 0x3e0293ee, v201
	v_exp_f32_e32 v201, v201
	s_cmp_eq_u64 vcc, exec
	s_cselect_b64 s[44:45], -1, 0
	s_waitcnt lgkmcnt(6)
	v_mfma_f32_32x32x16_bf16 v[48:63], v[76:79], v[92:95], v[48:63]
	ds_read_b64_tr_b16 v[92:93], v165 offset:13312
	ds_read_b64_tr_b16 v[94:95], v165 offset:15360
	v_cndmask_b32_e64 v202, v201, 1.0, s[44:45]
	v_cndmask_b32_e64 v203, v200, v203, s[44:45]
	v_mul_f32_e32 v248, 0xbe0293ee, v203
	v_fma_f32 v204, v204, s10, v248
	v_fma_f32 v205, v205, s10, v248
	v_fma_f32 v206, v206, s10, v248
	v_fma_f32 v207, v207, s10, v248
	s_waitcnt lgkmcnt(6)
	v_mfma_f32_32x32x16_bf16 v[16:31], v[64:67], v[80:83], v[16:31]
	ds_read_b64_tr_b16 v[80:81], v165 offset:1536
	ds_read_b64_tr_b16 v[82:83], v165 offset:3584
	v_fma_f32 v208, v208, s10, v248
	v_fma_f32 v209, v209, s10, v248
	v_fma_f32 v210, v210, s10, v248
	v_fma_f32 v211, v211, s10, v248
	v_fma_f32 v212, v212, s10, v248
	v_fma_f32 v213, v213, s10, v248
	v_fma_f32 v214, v214, s10, v248
	v_fma_f32 v215, v215, s10, v248
	s_waitcnt lgkmcnt(6)
	v_mfma_f32_32x32x16_bf16 v[16:31], v[68:71], v[84:87], v[16:31]
	ds_read_b64_tr_b16 v[84:85], v165 offset:5632
	ds_read_b64_tr_b16 v[86:87], v165 offset:7680
	v_fma_f32 v216, v216, s10, v248
	v_fma_f32 v217, v217, s10, v248
	v_fma_f32 v218, v218, s10, v248
	v_fma_f32 v219, v219, s10, v248
	v_fma_f32 v220, v220, s10, v248
	v_fma_f32 v221, v221, s10, v248
	v_fma_f32 v222, v222, s10, v248
	v_fma_f32 v223, v223, s10, v248
	v_fma_f32 v224, v224, s10, v248
	v_fma_f32 v225, v225, s10, v248
	s_waitcnt lgkmcnt(6)
	v_mfma_f32_32x32x16_bf16 v[16:31], v[72:75], v[88:91], v[16:31]
	ds_read_b64_tr_b16 v[88:89], v165 offset:9728
	ds_read_b64_tr_b16 v[90:91], v165 offset:11776
	v_fma_f32 v226, v226, s10, v248
	v_fma_f32 v227, v227, s10, v248
	v_fma_f32 v228, v228, s10, v248
	v_fma_f32 v229, v229, s10, v248
	v_fma_f32 v230, v230, s10, v248
	v_fma_f32 v231, v231, s10, v248
	v_fma_f32 v232, v232, s10, v248
	v_fma_f32 v233, v233, s10, v248
	v_fma_f32 v234, v234, s10, v248
	v_fma_f32 v235, v235, s10, v248
	s_waitcnt lgkmcnt(6)
	v_mfma_f32_32x32x16_bf16 v[16:31], v[76:79], v[92:95], v[16:31]
	ds_read_b64_tr_b16 v[92:93], v165 offset:13824
	ds_read_b64_tr_b16 v[94:95], v165 offset:15872
	v_exp_f32_e32 v204, v204
	v_exp_f32_e32 v205, v205
	v_exp_f32_e32 v206, v206
	v_exp_f32_e32 v207, v207
	s_waitcnt lgkmcnt(6)
	v_mfma_f32_32x32x16_bf16 v[0:15], v[64:67], v[80:83], v[0:15]
	v_exp_f32_e32 v208, v208
	v_exp_f32_e32 v209, v209
	v_pk_add_f32 v[170:171], v[204:205], v[206:207]
	v_exp_f32_e32 v210, v210
	v_exp_f32_e32 v211, v211
	s_waitcnt lgkmcnt(4)
	v_mfma_f32_32x32x16_bf16 v[0:15], v[68:71], v[84:87], v[0:15]
	v_pk_add_f32 v[170:171], v[170:171], v[208:209]
	v_exp_f32_e32 v212, v212
	v_exp_f32_e32 v213, v213
	v_pk_add_f32 v[170:171], v[170:171], v[210:211]
	v_exp_f32_e32 v214, v214
	s_waitcnt lgkmcnt(2)
	v_mfma_f32_32x32x16_bf16 v[0:15], v[72:75], v[88:91], v[0:15]
	v_exp_f32_e32 v215, v215
	v_pk_add_f32 v[170:171], v[170:171], v[212:213]
	v_exp_f32_e32 v216, v216
	v_exp_f32_e32 v217, v217
	s_waitcnt lgkmcnt(0)
	v_mfma_f32_32x32x16_bf16 v[0:15], v[76:79], v[92:95], v[0:15]
	v_pk_add_f32 v[170:171], v[170:171], v[214:215]
	v_exp_f32_e32 v218, v218
	v_exp_f32_e32 v219, v219
	v_pk_add_f32 v[170:171], v[170:171], v[216:217]
	v_cmp_gt_f32_e32 vcc, 1.0, v202
	s_cbranch_vccz .Lat_nro
	s_nop 7
	s_nop 7
	s_and_saveexec_b64 s[4:5], s[0:1]
	ds_write_b32 v183, v202
	s_or_b64 exec, exec, s[4:5]
	s_waitcnt lgkmcnt(0)
	ds_read_b128 v[244:247], v177 offset:0
	s_waitcnt lgkmcnt(0)
	v_pk_mul_f32 v[32:33], v[32:33], v[244:245]
	v_pk_mul_f32 v[34:35], v[34:35], v[246:247]
	v_pk_mul_f32 v[48:49], v[48:49], v[244:245]
	v_pk_mul_f32 v[50:51], v[50:51], v[246:247]
	v_pk_mul_f32 v[16:17], v[16:17], v[244:245]
	v_pk_mul_f32 v[18:19], v[18:19], v[246:247]
	v_pk_mul_f32 v[0:1], v[0:1], v[244:245]
	v_pk_mul_f32 v[2:3], v[2:3], v[246:247]
	ds_read_b128 v[244:247], v177 offset:32
	s_waitcnt lgkmcnt(0)
	v_pk_mul_f32 v[36:37], v[36:37], v[244:245]
	v_pk_mul_f32 v[38:39], v[38:39], v[246:247]
	v_pk_mul_f32 v[52:53], v[52:53], v[244:245]
	v_pk_mul_f32 v[54:55], v[54:55], v[246:247]
	v_pk_mul_f32 v[20:21], v[20:21], v[244:245]
	v_pk_mul_f32 v[22:23], v[22:23], v[246:247]
	v_pk_mul_f32 v[4:5], v[4:5], v[244:245]
	v_pk_mul_f32 v[6:7], v[6:7], v[246:247]
	ds_read_b128 v[244:247], v177 offset:64
	s_waitcnt lgkmcnt(0)
	v_pk_mul_f32 v[40:41], v[40:41], v[244:245]
	v_pk_mul_f32 v[42:43], v[42:43], v[246:247]
	v_pk_mul_f32 v[56:57], v[56:57], v[244:245]
	v_pk_mul_f32 v[58:59], v[58:59], v[246:247]
	v_pk_mul_f32 v[24:25], v[24:25], v[244:245]
	v_pk_mul_f32 v[26:27], v[26:27], v[246:247]
	v_pk_mul_f32 v[8:9], v[8:9], v[244:245]
	v_pk_mul_f32 v[10:11], v[10:11], v[246:247]
	ds_read_b128 v[244:247], v177 offset:96
	s_waitcnt lgkmcnt(0)
	v_pk_mul_f32 v[44:45], v[44:45], v[244:245]
	v_pk_mul_f32 v[46:47], v[46:47], v[246:247]
	v_pk_mul_f32 v[60:61], v[60:61], v[244:245]
	v_pk_mul_f32 v[62:63], v[62:63], v[246:247]
	v_pk_mul_f32 v[28:29], v[28:29], v[244:245]
	v_pk_mul_f32 v[30:31], v[30:31], v[246:247]
	v_pk_mul_f32 v[12:13], v[12:13], v[244:245]
	v_pk_mul_f32 v[14:15], v[14:15], v[246:247]
